# P4 epilogue: output stores marked nt (streaming)
# baseline (speedup 1.0000x reference)
;     __device__ __forceinline__ void operator()(const f32x4 (&acc)[2][2][4][2], const pg8::Unit& u, int wr, int wc, int fr, int fq) const {
;         const float* gate = (const float*)(KWS + WS_MOD) + 4096; const float* gb = KIN(I_BADA) + 4096;
;         const float* x = KIN(I_X); float* out = KOUT;
;         const int col0 = 256 * u.pn + 32 * wc + 4 * fq;
;         f32x4 gv[2][2];
; #pragma unroll
;         for (int bj = 0; bj < 2; ++bj)
; #pragma unroll
;             for (int n = 0; n < 2; ++n) gv[bj][n] = *(const f32x4*)(gate + col0 + 128 * bj + 16 * n) + *(const f32x4*)(gb + col0 + 128 * bj + 16 * n);
; #pragma unroll
;         for (int ai = 0; ai < 2; ++ai)
; #pragma unroll
;             for (int mh = 0; mh < 2; ++mh) {
;                 f32x4 xv[2][2][2];
; #pragma unroll
;                 for (int mm = 0; mm < 2; ++mm) {
;                     const size_t off = (size_t)(256 * u.pm + 128 * ai + 64 * wr + 16 * (2 * mh + mm) + fr) * DM + col0;
; #pragma unroll
;                     for (int bj = 0; bj < 2; ++bj)
; #pragma unroll
;                         for (int n = 0; n < 2; ++n) xv[mm][bj][n] = __builtin_nontemporal_load((const f32x4*)(x + off + 128 * bj + 16 * n));
;                 }
; #pragma unroll
;                 for (int mm = 0; mm < 2; ++mm) {
;                     const size_t off = (size_t)(256 * u.pm + 128 * ai + 64 * wr + 16 * (2 * mh + mm) + fr) * DM + col0;
; #pragma unroll
;                     for (int bj = 0; bj < 2; ++bj)
; #pragma unroll
;                         for (int n = 0; n < 2; ++n) *(f32x4*)(out + off + 128 * bj + 16 * n) = xv[mm][bj][n] + gv[bj][n] * acc[ai][bj][2 * mh + mm][n];
;                 }
.LBB0_904:
	v_lshl_or_b32 v136, s45, 8, v160
	v_ashrrev_i32_e32 v137, 31, v136
	s_load_dwordx2 s[20:21], s[0:1], 0xa8
	s_waitcnt lgkmcnt(0)
	v_lshlrev_b64 v[140:141], 2, v[136:137]
	s_load_dwordx2 s[24:25], s[0:1], 40
	s_waitcnt lgkmcnt(0)
	v_lshl_add_u64 v[136:137], s[20:21], 0, v[140:141]
	s_load_dwordx2 s[46:47], s[0:1], 0
	s_waitcnt lgkmcnt(0)
	v_lshl_add_u64 v[138:139], v[136:137], 0, s[10:11]
	v_add_co_u32_e32 v136, vcc, 0x4000, v136
	s_load_dwordx2 s[18:19], s[0:1], 0xa0
	s_waitcnt lgkmcnt(0)
	v_lshl_add_u64 v[142:143], s[24:25], 0, v[140:141]
	s_nop 0
	v_addc_co_u32_e32 v137, vcc, 0, v137, vcc
	global_load_dwordx4 v[164:167], v[136:137], off
	v_add_co_u32_e32 v136, vcc, 0x4000, v142
	v_lshl_add_u64 v[150:151], v[142:143], 0, s[10:11]
	s_nop 0
	v_addc_co_u32_e32 v137, vcc, 0, v143, vcc
	global_load_dwordx4 v[168:171], v[136:137], off
	global_load_dwordx4 v[142:145], v[138:139], off offset:64
	global_load_dwordx4 v[146:149], v[138:139], off offset:512
	global_load_dwordx4 v[154:157], v[150:151], off offset:64
	global_load_dwordx4 v[172:175], v[150:151], off offset:512
	global_load_dwordx4 v[176:179], v[138:139], off offset:576
	global_load_dwordx4 v[180:183], v[150:151], off offset:576
	v_lshl_add_u32 v138, s44, 8, v158
	v_ashrrev_i32_e32 v139, 31, v138
	v_lshl_add_u64 v[136:137], s[46:47], 0, v[140:141]
	v_lshlrev_b64 v[150:151], 13, v[138:139]
	v_or_b32_e32 v196, 16, v138
	v_lshl_add_u64 v[152:153], v[136:137], 0, v[150:151]
	v_ashrrev_i32_e32 v197, 31, v196
	global_load_dwordx4 v[184:187], v[152:153], off offset:64 nt
	global_load_dwordx4 v[188:191], v[152:153], off offset:512 nt
	global_load_dwordx4 v[192:195], v[152:153], off offset:576 nt
	v_lshlrev_b64 v[216:217], 13, v[196:197]
	v_lshl_add_u64 v[212:213], v[136:137], 0, v[216:217]
	global_load_dwordx4 v[196:199], v[212:213], off offset:64 nt
	global_load_dwordx4 v[200:203], v[212:213], off offset:512 nt
	global_load_dwordx4 v[204:207], v[212:213], off offset:576 nt
	global_load_dwordx4 v[208:211], v[152:153], off nt
	s_nop 0
	global_load_dwordx4 v[212:215], v[212:213], off nt
	v_or_b32_e32 v152, 32, v138
	v_ashrrev_i32_e32 v153, 31, v152
	v_lshlrev_b64 v[218:219], 13, v[152:153]
	v_lshl_add_u64 v[152:153], s[18:19], 0, v[140:141]
	v_lshl_add_u64 v[222:223], v[152:153], 0, v[150:151]
	v_lshl_add_u64 v[216:217], v[152:153], 0, v[216:217]
	v_lshl_add_u64 v[220:221], v[136:137], 0, v[218:219]
	s_andn2_b64 vcc, exec, s[16:17]
	s_mov_b64 s[16:17], -1
	s_waitcnt vmcnt(0)
	v_pk_add_f32 v[140:141], v[144:145], v[156:157]
	v_pk_add_f32 v[142:143], v[142:143], v[154:155]
	v_pk_add_f32 v[146:147], v[146:147], v[172:173]
	v_pk_add_f32 v[144:145], v[148:149], v[174:175]
	v_pk_add_f32 v[148:149], v[178:179], v[182:183]
	v_pk_add_f32 v[150:151], v[176:177], v[180:181]
	v_pk_add_f32 v[154:155], v[166:167], v[170:171]
	v_pk_add_f32 v[156:157], v[164:165], v[168:169]
	v_add_u32_e32 v166, 0x80, v138
	v_pk_fma_f32 v[126:127], v[126:127], v[140:141], v[186:187]
	v_pk_fma_f32 v[124:125], v[124:125], v[142:143], v[184:185]
	v_pk_fma_f32 v[108:109], v[108:109], v[146:147], v[188:189]
	v_pk_fma_f32 v[110:111], v[110:111], v[144:145], v[190:191]
	v_pk_fma_f32 v[106:107], v[106:107], v[148:149], v[194:195]
	v_pk_fma_f32 v[104:105], v[104:105], v[150:151], v[192:193]
	global_store_dwordx4 v[222:223], v[124:127], off offset:64 nt
	global_store_dwordx4 v[222:223], v[108:111], off offset:512 nt
	global_store_dwordx4 v[222:223], v[104:107], off offset:576 nt
	v_pk_fma_f32 v[118:119], v[118:119], v[140:141], v[198:199]
	v_or_b32_e32 v108, 48, v138
	v_pk_fma_f32 v[116:117], v[116:117], v[142:143], v[196:197]
	v_ashrrev_i32_e32 v109, 31, v108
	v_pk_fma_f32 v[102:103], v[102:103], v[144:145], v[202:203]
	v_pk_fma_f32 v[100:101], v[100:101], v[146:147], v[200:201]
	v_pk_fma_f32 v[98:99], v[98:99], v[148:149], v[206:207]
	v_pk_fma_f32 v[96:97], v[96:97], v[150:151], v[204:205]
	v_pk_fma_f32 v[122:123], v[122:123], v[154:155], v[210:211]
	v_pk_fma_f32 v[120:121], v[120:121], v[156:157], v[208:209]
	v_pk_fma_f32 v[106:107], v[114:115], v[154:155], v[214:215]
	v_pk_fma_f32 v[104:105], v[112:113], v[156:157], v[212:213]
	global_store_dwordx4 v[216:217], v[116:119], off offset:64 nt
	global_store_dwordx4 v[216:217], v[100:103], off offset:512 nt
	global_store_dwordx4 v[216:217], v[96:99], off offset:576 nt
	global_store_dwordx4 v[222:223], v[120:123], off nt
	global_store_dwordx4 v[216:217], v[104:107], off nt
	v_lshlrev_b64 v[164:165], 13, v[108:109]
	global_load_dwordx4 v[96:99], v[220:221], off nt
	global_load_dwordx4 v[100:103], v[220:221], off offset:64 nt
	global_load_dwordx4 v[104:107], v[220:221], off offset:512 nt
	global_load_dwordx4 v[108:111], v[220:221], off offset:576 nt
	v_lshl_add_u64 v[124:125], v[136:137], 0, v[164:165]
	global_load_dwordx4 v[112:115], v[124:125], off nt
	global_load_dwordx4 v[116:119], v[124:125], off offset:64 nt
	global_load_dwordx4 v[120:123], v[124:125], off offset:512 nt
	s_nop 0
	global_load_dwordx4 v[124:127], v[124:125], off offset:576 nt
	v_lshl_add_u64 v[170:171], v[152:153], 0, v[218:219]
	v_ashrrev_i32_e32 v167, 31, v166
	v_lshl_add_u64 v[164:165], v[152:153], 0, v[164:165]
	v_lshlrev_b64 v[166:167], 13, v[166:167]
	v_lshl_add_u64 v[168:169], v[136:137], 0, v[166:167]
	s_waitcnt vmcnt(7)
	v_pk_fma_f32 v[94:95], v[94:95], v[154:155], v[98:99]
	v_pk_fma_f32 v[92:93], v[92:93], v[156:157], v[96:97]
	s_waitcnt vmcnt(5)
	v_pk_fma_f32 v[76:77], v[76:77], v[146:147], v[104:105]
	v_pk_fma_f32 v[90:91], v[90:91], v[140:141], v[102:103]
	v_pk_fma_f32 v[88:89], v[88:89], v[142:143], v[100:101]
	v_pk_fma_f32 v[78:79], v[78:79], v[144:145], v[106:107]
	s_waitcnt vmcnt(4)
; #define PG8_BAR __builtin_amdgcn_s_barrier()
; template <class Epi, class Sched>
; __device__ __forceinline__ void gemm_phase(LAS unsigned char* lds, const Sched& S, const Epi& E) {
;     ...
;         if (!has_next) break;
; #pragma unroll
;         for (int a = 0; a < 2; ++a)
; #pragma unroll
;             for (int b = 0; b < 2; ++b)
; #pragma unroll
;                 for (int m = 0; m < 4; ++m)
; #pragma unroll
;                     for (int n = 0; n < 2; ++n) acc[a][b][m][n] = (f32x4){0.f, 0.f, 0.f, 0.f};
;         cur = nxt; cA = nA; cB = nB; ++ui;
;         if (wr == 1) PG8_BAR;
;     __device__ __forceinline__ void operator()(const f32x4 (&acc)[2][2][4][2], const pg8::Unit& u, int wr, int wc, int fr, int fq) const {
;     ...
;         for (int ai = 0; ai < 2; ++ai)
; #pragma unroll
;             for (int mh = 0; mh < 2; ++mh) {
;                 f32x4 xv[2][2][2];
; #pragma unroll
;                 for (int mm = 0; mm < 2; ++mm) {
;                     const size_t off = (size_t)(256 * u.pm + 128 * ai + 64 * wr + 16 * (2 * mh + mm) + fr) * DM + col0;
; #pragma unroll
;                     for (int bj = 0; bj < 2; ++bj)
; #pragma unroll
;                         for (int n = 0; n < 2; ++n) xv[mm][bj][n] = __builtin_nontemporal_load((const f32x4*)(x + off + 128 * bj + 16 * n));
;                 }
; #pragma unroll
;                 for (int mm = 0; mm < 2; ++mm) {
;                     const size_t off = (size_t)(256 * u.pm + 128 * ai + 64 * wr + 16 * (2 * mh + mm) + fr) * DM + col0;
; #pragma unroll
;                     for (int bj = 0; bj < 2; ++bj)
; #pragma unroll
;                         for (int n = 0; n < 2; ++n) *(f32x4*)(out + off + 128 * bj + 16 * n) = xv[mm][bj][n] + gv[bj][n] * acc[ai][bj][2 * mh + mm][n];
;                 }
	v_pk_fma_f32 v[74:75], v[74:75], v[148:149], v[110:111]
	v_pk_fma_f32 v[72:73], v[72:73], v[150:151], v[108:109]
	s_waitcnt vmcnt(3)
	v_pk_fma_f32 v[86:87], v[86:87], v[154:155], v[114:115]
	v_pk_fma_f32 v[84:85], v[84:85], v[156:157], v[112:113]
	s_waitcnt vmcnt(2)
	v_pk_fma_f32 v[82:83], v[82:83], v[140:141], v[118:119]
	v_pk_fma_f32 v[80:81], v[80:81], v[142:143], v[116:117]
	s_waitcnt vmcnt(1)
	v_pk_fma_f32 v[70:71], v[70:71], v[144:145], v[122:123]
	v_pk_fma_f32 v[68:69], v[68:69], v[146:147], v[120:121]
	s_waitcnt vmcnt(0)
	v_pk_fma_f32 v[66:67], v[66:67], v[148:149], v[126:127]
	v_pk_fma_f32 v[64:65], v[64:65], v[150:151], v[124:125]
	global_store_dwordx4 v[170:171], v[92:95], off nt
	global_store_dwordx4 v[170:171], v[88:91], off offset:64 nt
	global_store_dwordx4 v[170:171], v[76:79], off offset:512 nt
	global_store_dwordx4 v[170:171], v[72:75], off offset:576 nt
	global_store_dwordx4 v[164:165], v[84:87], off nt
	global_store_dwordx4 v[164:165], v[80:83], off offset:64 nt
	global_store_dwordx4 v[164:165], v[68:71], off offset:512 nt
	global_store_dwordx4 v[164:165], v[64:67], off offset:576 nt
	v_add_u32_e32 v76, 0x90, v138
	v_ashrrev_i32_e32 v77, 31, v76
	v_lshlrev_b64 v[96:97], 13, v[76:77]
	global_load_dwordx4 v[64:67], v[168:169], off nt
	global_load_dwordx4 v[68:71], v[168:169], off offset:64 nt
	global_load_dwordx4 v[72:75], v[168:169], off offset:512 nt
	global_load_dwordx4 v[76:79], v[168:169], off offset:576 nt
	v_lshl_add_u64 v[92:93], v[136:137], 0, v[96:97]
	global_load_dwordx4 v[80:83], v[92:93], off nt
	global_load_dwordx4 v[84:87], v[92:93], off offset:64 nt
	global_load_dwordx4 v[88:91], v[92:93], off offset:512 nt
	s_nop 0
	global_load_dwordx4 v[92:95], v[92:93], off offset:576 nt
	v_add_u32_e32 v98, 0xa0, v138
	v_lshl_add_u64 v[102:103], v[152:153], 0, v[166:167]
	v_ashrrev_i32_e32 v99, 31, v98
	v_lshl_add_u64 v[96:97], v[152:153], 0, v[96:97]
	v_lshlrev_b64 v[98:99], 13, v[98:99]
	v_lshl_add_u64 v[100:101], v[136:137], 0, v[98:99]
	s_waitcnt vmcnt(7)
	v_pk_fma_f32 v[62:63], v[62:63], v[154:155], v[66:67]
	v_pk_fma_f32 v[60:61], v[60:61], v[156:157], v[64:65]
	s_waitcnt vmcnt(5)
	v_pk_fma_f32 v[44:45], v[44:45], v[146:147], v[72:73]
	v_pk_fma_f32 v[58:59], v[58:59], v[140:141], v[70:71]
	v_pk_fma_f32 v[56:57], v[56:57], v[142:143], v[68:69]
	v_pk_fma_f32 v[46:47], v[46:47], v[144:145], v[74:75]
	s_waitcnt vmcnt(4)
	v_pk_fma_f32 v[42:43], v[42:43], v[148:149], v[78:79]
	v_pk_fma_f32 v[40:41], v[40:41], v[150:151], v[76:77]
	s_waitcnt vmcnt(3)
	v_pk_fma_f32 v[54:55], v[54:55], v[154:155], v[82:83]
	v_pk_fma_f32 v[52:53], v[52:53], v[156:157], v[80:81]
	s_waitcnt vmcnt(2)
	v_pk_fma_f32 v[50:51], v[50:51], v[140:141], v[86:87]
	v_pk_fma_f32 v[48:49], v[48:49], v[142:143], v[84:85]
	s_waitcnt vmcnt(1)
	v_pk_fma_f32 v[38:39], v[38:39], v[144:145], v[90:91]
	v_pk_fma_f32 v[36:37], v[36:37], v[146:147], v[88:89]
	s_waitcnt vmcnt(0)
	v_pk_fma_f32 v[34:35], v[34:35], v[148:149], v[94:95]
	v_pk_fma_f32 v[32:33], v[32:33], v[150:151], v[92:93]
	global_store_dwordx4 v[102:103], v[60:63], off nt
	global_store_dwordx4 v[102:103], v[56:59], off offset:64 nt
	global_store_dwordx4 v[102:103], v[44:47], off offset:512 nt
	global_store_dwordx4 v[102:103], v[40:43], off offset:576 nt
	global_store_dwordx4 v[96:97], v[52:55], off nt
	global_store_dwordx4 v[96:97], v[48:51], off offset:64 nt
	global_store_dwordx4 v[96:97], v[36:39], off offset:512 nt
	global_store_dwordx4 v[96:97], v[32:35], off offset:576 nt
	v_add_u32_e32 v44, 0xb0, v138
	v_ashrrev_i32_e32 v45, 31, v44
	v_lshlrev_b64 v[64:65], 13, v[44:45]
	global_load_dwordx4 v[32:35], v[100:101], off nt
	global_load_dwordx4 v[36:39], v[100:101], off offset:64 nt
	v_lshl_add_u64 v[66:67], v[136:137], 0, v[64:65]
	global_load_dwordx4 v[40:43], v[100:101], off offset:512 nt
	global_load_dwordx4 v[44:47], v[100:101], off offset:576 nt
	global_load_dwordx4 v[48:51], v[66:67], off nt
	global_load_dwordx4 v[52:55], v[66:67], off offset:64 nt
	global_load_dwordx4 v[56:59], v[66:67], off offset:512 nt
	global_load_dwordx4 v[60:63], v[66:67], off offset:576 nt
	v_lshl_add_u64 v[66:67], v[152:153], 0, v[98:99]
	v_lshl_add_u64 v[64:65], v[152:153], 0, v[64:65]
	s_waitcnt vmcnt(7)
	v_pk_fma_f32 v[30:31], v[30:31], v[154:155], v[34:35]
	v_pk_fma_f32 v[28:29], v[28:29], v[156:157], v[32:33]
	s_waitcnt vmcnt(6)
	v_pk_fma_f32 v[26:27], v[26:27], v[140:141], v[38:39]
	v_pk_fma_f32 v[24:25], v[24:25], v[142:143], v[36:37]
	s_waitcnt vmcnt(5)
	v_pk_fma_f32 v[14:15], v[14:15], v[144:145], v[42:43]
	v_pk_fma_f32 v[12:13], v[12:13], v[146:147], v[40:41]
	s_waitcnt vmcnt(4)
	v_pk_fma_f32 v[10:11], v[10:11], v[148:149], v[46:47]
	v_pk_fma_f32 v[8:9], v[8:9], v[150:151], v[44:45]
	s_waitcnt vmcnt(3)
	v_pk_fma_f32 v[22:23], v[22:23], v[154:155], v[50:51]
	v_pk_fma_f32 v[20:21], v[20:21], v[156:157], v[48:49]
	s_waitcnt vmcnt(2)
	v_pk_fma_f32 v[18:19], v[18:19], v[140:141], v[54:55]
	v_pk_fma_f32 v[16:17], v[16:17], v[142:143], v[52:53]
	s_waitcnt vmcnt(1)
	v_pk_fma_f32 v[6:7], v[6:7], v[144:145], v[58:59]
	v_pk_fma_f32 v[4:5], v[4:5], v[146:147], v[56:57]
	s_waitcnt vmcnt(0)
	v_pk_fma_f32 v[2:3], v[2:3], v[148:149], v[62:63]
	v_pk_fma_f32 v[0:1], v[0:1], v[150:151], v[60:61]
	global_store_dwordx4 v[66:67], v[28:31], off nt
	global_store_dwordx4 v[66:67], v[24:27], off offset:64 nt
	global_store_dwordx4 v[66:67], v[12:15], off offset:512 nt
	global_store_dwordx4 v[66:67], v[8:11], off offset:576 nt
	global_store_dwordx4 v[64:65], v[20:23], off nt
	global_store_dwordx4 v[64:65], v[16:19], off offset:64 nt
	global_store_dwordx4 v[64:65], v[4:7], off offset:512 nt
	global_store_dwordx4 v[64:65], v[0:3], off offset:576 nt
	s_cbranch_vccnz .LBB0_897
	s_andn2_b64 vcc, exec, s[4:5]
	s_cbranch_vccnz .LBB0_896
	s_barrier
	s_branch .LBB0_896
